# NA item prologue: Q-row loads issued before the rpb-table round trips
# baseline (speedup 1.0000x reference)
.LBB0_183:
	s_abs_i32 s1, s23
	s_mul_hi_u32 s4, s1, s92
	s_mul_i32 s5, s4, s90
	s_ashr_i32 s0, s23, 31
	s_sub_i32 s1, s1, s5
	s_xor_b32 s0, s0, s91
	s_add_i32 s5, s4, 1
	s_sub_i32 s6, s1, s90
	s_cmp_ge_u32 s1, s90
	s_cselect_b32 s4, s5, s4
	s_cselect_b32 s1, s6, s1
	s_add_i32 s5, s4, 1
	s_cmp_ge_u32 s1, s90
	s_cselect_b32 s1, s5, s4
	s_xor_b32 s1, s1, s0
	s_sub_i32 s4, s1, s0
	s_and_b32 s5, s4, 15
	s_waitcnt lgkmcnt(0)
	s_barrier
	s_mul_i32 s6, s4, s21
	s_sub_i32 s6, s23, s6
	s_cmp_lt_i32 s6, 16
	s_movk_i32 s7, 0xf800
	s_cselect_b32 s7, 0x100, s7
	s_lshl_b32 s6, s6, 7
	s_add_i32 s101, s7, s6
	s_ashr_i32 s6, s4, 4
	s_mul_i32 s6, s6, 0x900
	s_add_i32 s101, s101, s6
	s_lshl_b32 s100, s5, 6
	v_or_b32_e32 v6, s100, v90
	v_add_u32_e32 v0, s101, v101
	v_lshl_or_b32 v0, v0, 10, v6
	v_lshl_add_u64 v[2:3], v[0:1], 1, s[26:27]
	global_load_dwordx4 v[200:203], v[2:3], off
	v_add_u32_e32 v0, s101, v102
	v_lshl_or_b32 v0, v0, 10, v6
	v_lshl_add_u64 v[2:3], v[0:1], 1, s[26:27]
	global_load_dwordx4 v[204:207], v[2:3], off
	v_add_u32_e32 v0, s101, v103
	v_lshl_or_b32 v0, v0, 10, v6
	v_lshl_add_u64 v[2:3], v[0:1], 1, s[26:27]
	global_load_dwordx4 v[208:211], v[2:3], off
	v_add_u32_e32 v0, s101, v104
	v_lshl_or_b32 v0, v0, 10, v6
	v_lshl_add_u64 v[2:3], v[0:1], 1, s[26:27]
	global_load_dwordx4 v[212:215], v[2:3], off
	s_and_saveexec_b64 s[0:1], s[38:39]
	s_cbranch_execz .LBB0_193
	s_mov_b64 s[80:81], -1
	v_mov_b32_e32 v2, v134
	v_mov_b32_e32 v0, v113
	s_and_saveexec_b64 s[24:25], s[60:61]
	s_cbranch_execz .LBB0_190
	s_or_b32 s6, s18, s5
	s_mov_b32 s9, s62
	s_mov_b64 s[56:57], s[60:61]
	s_mul_i32 s7, s19, 0x744
	s_mul_hi_u32 s8, s6, 0x744
	v_readlane_b32 s60, v253, 20
	s_add_i32 s8, s8, s7
	s_mulk_i32 s6, 0x744
	v_readlane_b32 s74, v253, 34
	v_readlane_b32 s75, v253, 35
	s_add_u32 s80, s74, s6
	s_addc_u32 s81, s75, s8
	s_mov_b64 s[82:83], 0
	v_mov_b32_e32 v0, v111
	v_mov_b32_e32 v4, v114
	v_mov_b64_e32 v[2:3], v[134:135]
	v_readlane_b32 s61, v253, 21
	v_readlane_b32 s62, v253, 22
	v_readlane_b32 s63, v253, 23
	v_readlane_b32 s64, v253, 24
	v_readlane_b32 s65, v253, 25
	v_readlane_b32 s66, v253, 26
	v_readlane_b32 s67, v253, 27
	v_readlane_b32 s68, v253, 28
	v_readlane_b32 s69, v253, 29
	v_readlane_b32 s70, v253, 30
	v_readlane_b32 s71, v253, 31
	v_readlane_b32 s72, v253, 32
	v_readlane_b32 s73, v253, 33

.LBB0_193:
	s_or_b64 exec, exec, s[0:1]
	s_mul_i32 s0, s4, s21
	s_sub_i32 s1, s23, s0
	s_lshl_b32 s0, s1, 1
	s_max_i32 s6, s0, 4
	s_add_i32 s6, s6, -4
	s_min_u32 s80, s6, 24
	s_max_i32 s6, s0, 3
	s_add_i32 s6, s6, -3
	s_min_u32 s6, s6, 24
	s_ashr_i32 s7, s4, 4
	s_add_i32 s6, s6, 7
	s_cmp_lt_i32 s1, 16
	s_movk_i32 s8, 0xf800
	s_cselect_b32 s81, s80, 0
	s_cselect_b32 s6, s6, -1
	s_cselect_b32 s8, 0x100, s8
	s_lshl_b32 s1, s1, 7
	s_sub_i32 s82, s6, s81
	s_mul_i32 s6, s7, 0x900
	s_add_i32 s25, s8, s1
	s_add_i32 s25, s25, s6
	s_lshl_b32 s24, s5, 6
	v_or_b32_e32 v6, s24, v90
	s_lshl_b32 s1, s81, 6
	s_not_b32 s5, s82
	s_addk_i32 s1, 0x100
	s_lshl_b32 s5, s5, 6
	s_cmp_lt_i32 s82, 0
	s_cselect_b32 s5, s5, s1
	v_add_u32_e32 v122, s6, v91
	v_readfirstlane_b32 s1, v94
	s_mov_b32 m0, s1
	s_lshl_b32 s1, s7, 10
	s_or_b32 s7, s24, s1
	v_add_u32_e32 v123, s6, v98
	s_mov_b32 s83, 0
	s_cmp_gt_i32 s82, -5
	v_add_lshl_u32 v0, s5, v122, 10
	v_or3_b32 v0, v0, s24, v92
	v_lshl_add_u64 v[2:3], v[0:1], 1, s[28:29]
	v_add_u32_e32 v0, s7, v97
	v_mul_lo_u32 v0, v0, s96
	v_or_b32_e32 v0, v0, v92
	v_add_u32_e32 v0, s5, v0
	global_load_lds_dwordx4 v[2:3], off
	v_lshl_add_u64 v[2:3], v[0:1], 1, s[58:59]
	v_add_u32_e32 v0, 0x2000, v94
	s_nop 0
	v_readfirstlane_b32 s8, v0
	v_add_lshl_u32 v0, s5, v123, 10
	s_mov_b32 m0, s8
	v_or3_b32 v0, v0, s24, v99
	global_load_lds_dwordx4 v[2:3], off
	v_lshl_add_u64 v[2:3], v[0:1], 1, s[28:29]
	v_add_u32_e32 v0, 0x400, v94
	s_nop 0
	v_readfirstlane_b32 s6, v0
	v_add_u32_e32 v0, s7, v100
	v_mul_lo_u32 v0, v0, s96
	v_or_b32_e32 v124, v0, v99
	s_mov_b32 m0, s6
	v_add_u32_e32 v0, s5, v124
	global_load_lds_dwordx4 v[2:3], off
	v_lshl_add_u64 v[2:3], v[0:1], 1, s[58:59]
	v_add_u32_e32 v0, 0x2400, v94
	s_nop 0
	v_readfirstlane_b32 s5, v0
	s_mov_b32 m0, s5
	s_nop 0
	global_load_lds_dwordx4 v[2:3], off
	s_waitcnt vmcnt(4)
	ds_write_b128 v118, v[200:203] offset:32768
	ds_write_b128 v119, v[204:207] offset:32768
	ds_write_b128 v120, v[208:211] offset:32768
	ds_write_b128 v121, v[212:215] offset:32768
	s_waitcnt vmcnt(0) lgkmcnt(0)
	s_barrier
	s_cbranch_scc0 .LBB0_181
	s_or_b32 s0, s0, 1
	s_max_i32 s0, s0, 4
	s_add_i32 s0, s0, -4
	s_min_u32 s56, s0, 24
	s_mul_i32 s0, s62, s4
	v_or_b32_e32 v0, s1, v95
	s_add_i32 s0, s81, s0
	s_lshl_b32 s1, s23, 1
	s_sub_i32 s0, s0, s1
	s_mul_i32 s1, s21, 0xf8
	v_add3_u32 v0, v96, s24, v0
	s_mul_i32 s1, s1, s4
	s_mul_i32 s4, s81, 0x7c
	v_mul_lo_u32 v0, v0, s96
	s_add_i32 s1, s1, s4
	s_mul_i32 s4, s23, 0xf8
	v_mov_b32_e32 v12, v1
	v_mov_b32_e32 v13, v1
	v_or_b32_e32 v125, v0, v92
	s_mulk_i32 s0, 0x7c
	s_sub_i32 s1, s1, s4
	v_mov_b32_e32 v0, v1
	v_mov_b32_e32 v10, v1
	v_mov_b32_e32 v11, v1
	v_mov_b32_e32 v74, 0xe0ad78ec
	v_mov_b64_e32 v[20:21], v[12:13]
	v_mov_b64_e32 v[28:29], v[12:13]
	v_mov_b64_e32 v[32:33], v[12:13]
	v_mov_b64_e32 v[16:17], v[12:13]
	v_mov_b64_e32 v[24:25], v[12:13]
	v_mov_b64_e32 v[36:37], v[12:13]
	v_mov_b64_e32 v[40:41], v[12:13]
	s_add_i32 s88, s82, 1
	s_add_i32 s89, s80, 8
	s_add_i32 s57, s56, 8
	s_add_i32 s22, s82, 4
	s_add_i32 s96, s82, 5
	v_or_b32_e32 v126, s24, v92
	v_or_b32_e32 v127, s24, v99
	s_add_i32 s97, s0, 0x103e0
	v_add_u32_e32 v128, s1, v115
	s_add_i32 s98, s0, 0x103e4
	s_add_i32 s99, s0, 0x103e8
	s_add_i32 s30, s0, 0x103ec
	s_add_i32 s4, s0, 0x10420
	v_mov_b64_e32 v[18:19], v[10:11]
	v_mov_b64_e32 v[26:27], v[10:11]
	v_mov_b64_e32 v[30:31], v[10:11]
	v_mov_b64_e32 v[14:15], v[10:11]
	v_mov_b64_e32 v[22:23], v[10:11]
	v_mov_b64_e32 v[34:35], v[10:11]
	v_mov_b64_e32 v[38:39], v[10:11]
	s_mov_b32 s8, 0
	v_mov_b64_e32 v[78:79], v[0:1]
	v_mov_b32_e32 v75, v74
